# MLP1A K loop software-pipelined per wave (fragment reads of next half interleaved with MFMAs, 4-deep DMA ring, 1 barrier per K-step, no group stagger)
# baseline (speedup 1.0000x reference)
.LBB0_731:
	v_lshrrev_b32_e32 v8, 30, v7
	v_add_u32_e32 v8, v7, v8
	v_ashrrev_i32_e32 v8, 2, v8
	v_mul_i32_i24_e32 v9, 4, v8
	v_lshrrev_b32_e32 v182, 5, v6
	v_lshrrev_b32_e32 v6, 2, v0
	v_sub_u32_e32 v7, v7, v9
	v_and_b32_e32 v9, 31, v0
	v_bfe_u32 v10, v0, 2, 2
	v_bitop3_b32 v6, v182, v6, 3 bitop3:0x78
	v_lshl_or_b32 v0, v8, 7, v9
	v_lshlrev_b32_e32 v193, 4, v6
	v_bitop3_b32 v6, v182, v10, 2 bitop3:0x36
	v_or_b32_e32 v8, 16, v4
	s_lshl_b32 s37, s54, 8
	v_lshlrev_b32_e32 v194, 4, v6
	v_or_b32_e32 v6, s37, v8
	v_lshlrev_b32_e32 v180, 6, v7
	v_add_u32_e32 v6, v6, v5
	s_lshl_b32 s52, s52, 12
	v_or_b32_e32 v7, v180, v9
	v_subrev_u32_e32 v6, s52, v6
	v_lshlrev_b32_e32 v192, 6, v7
	v_ashrrev_i32_e32 v7, 31, v6
	v_lshlrev_b64 v[6:7], 11, v[6:7]
	v_or_b32_e32 v6, v6, v2
	v_lshl_add_u64 v[184:185], s[48:49], 0, v[6:7]
	v_or_b32_e32 v6, s37, v4
	v_add_u32_e32 v6, v6, v5
	v_subrev_u32_e32 v6, s52, v6
	v_ashrrev_i32_e32 v7, 31, v6
	v_lshlrev_b64 v[6:7], 11, v[6:7]
	v_or_b32_e32 v6, v6, v2
	v_lshl_add_u64 v[186:187], s[48:49], 0, v[6:7]
	v_add3_u32 v6, v8, s36, v5
	v_add3_u32 v4, v4, s36, v5
	v_ashrrev_i32_e32 v7, 31, v6
	v_ashrrev_i32_e32 v5, 31, v4
	v_lshlrev_b64 v[6:7], 11, v[6:7]
	v_lshlrev_b64 v[4:5], 11, v[4:5]
	v_or_b32_e32 v6, v6, v2
	v_or_b32_e32 v4, v4, v2
	v_mov_b32_e32 v116, v144
	v_lshlrev_b32_e32 v181, 6, v0
	v_lshl_add_u64 v[188:189], s[50:51], 0, v[6:7]
	v_lshl_add_u64 v[190:191], s[50:51], 0, v[4:5]
	s_mov_b32 s55, 0x18000
	s_mov_b32 s56, 0
	s_mov_b64 s[36:37], 0
	s_mov_b32 s57, 0
	v_mov_b32_e32 v117, v145
	v_mov_b32_e32 v118, v146
	v_mov_b32_e32 v119, v147
	v_mov_b32_e32 v120, v148
	v_mov_b32_e32 v121, v149
	v_mov_b32_e32 v122, v150
	v_mov_b32_e32 v123, v151
	v_mov_b32_e32 v124, v152
	v_mov_b32_e32 v125, v153
	v_mov_b32_e32 v126, v154
	v_mov_b32_e32 v127, v155
	v_mov_b32_e32 v128, v156
	v_mov_b32_e32 v129, v157
	v_mov_b32_e32 v130, v158
	v_mov_b32_e32 v131, v159
	v_mov_b32_e32 v100, v160
	v_mov_b32_e32 v101, v161
	v_mov_b32_e32 v102, v162
	v_mov_b32_e32 v103, v163
	v_mov_b32_e32 v104, v164
	v_mov_b32_e32 v105, v165
	v_mov_b32_e32 v106, v166
	v_mov_b32_e32 v107, v167
	v_mov_b32_e32 v108, v168
	v_mov_b32_e32 v109, v169
	v_mov_b32_e32 v110, v170
	v_mov_b32_e32 v111, v171
	v_mov_b32_e32 v112, v172
	v_mov_b32_e32 v113, v173
	v_mov_b32_e32 v114, v174
	v_mov_b32_e32 v115, v175
	v_mov_b32_e32 v84, v144
	v_mov_b32_e32 v85, v145
	v_mov_b32_e32 v86, v146
	v_mov_b32_e32 v87, v147
	v_mov_b32_e32 v88, v148
	v_mov_b32_e32 v89, v149
	v_mov_b32_e32 v90, v150
	v_mov_b32_e32 v91, v151
	v_mov_b32_e32 v92, v152
	v_mov_b32_e32 v93, v153
	v_mov_b32_e32 v94, v154
	v_mov_b32_e32 v95, v155
	v_mov_b32_e32 v96, v156
	v_mov_b32_e32 v97, v157
	v_mov_b32_e32 v98, v158
	v_mov_b32_e32 v99, v159
	v_mov_b32_e32 v68, v160
	v_mov_b32_e32 v69, v161
	v_mov_b32_e32 v70, v162
	v_mov_b32_e32 v71, v163
	v_mov_b32_e32 v72, v164
	v_mov_b32_e32 v73, v165
	v_mov_b32_e32 v74, v166
	v_mov_b32_e32 v75, v167
	v_mov_b32_e32 v76, v168
	v_mov_b32_e32 v77, v169
	v_mov_b32_e32 v78, v170
	v_mov_b32_e32 v79, v171
	v_mov_b32_e32 v80, v172
	v_mov_b32_e32 v81, v173
	v_mov_b32_e32 v82, v174
	v_mov_b32_e32 v83, v175
	v_mov_b32_e32 v52, v144
	v_mov_b32_e32 v53, v145
	v_mov_b32_e32 v54, v146
	v_mov_b32_e32 v55, v147
	v_mov_b32_e32 v56, v148
	v_mov_b32_e32 v57, v149
	v_mov_b32_e32 v58, v150
	v_mov_b32_e32 v59, v151
	v_mov_b32_e32 v60, v152
	v_mov_b32_e32 v61, v153
	v_mov_b32_e32 v62, v154
	v_mov_b32_e32 v63, v155
	v_mov_b32_e32 v64, v156
	v_mov_b32_e32 v65, v157
	v_mov_b32_e32 v66, v158
	v_mov_b32_e32 v67, v159
	v_mov_b32_e32 v36, v160
	v_mov_b32_e32 v37, v161
	v_mov_b32_e32 v38, v162
	v_mov_b32_e32 v39, v163
	v_mov_b32_e32 v40, v164
	v_mov_b32_e32 v41, v165
	v_mov_b32_e32 v42, v166
	v_mov_b32_e32 v43, v167
	v_mov_b32_e32 v44, v168
	v_mov_b32_e32 v45, v169
	v_mov_b32_e32 v46, v170
	v_mov_b32_e32 v47, v171
	v_mov_b32_e32 v48, v172
	v_mov_b32_e32 v49, v173
	v_mov_b32_e32 v50, v174
	v_mov_b32_e32 v51, v175
	v_mov_b32_e32 v20, v144
	v_mov_b32_e32 v21, v145
	v_mov_b32_e32 v22, v146
	v_mov_b32_e32 v23, v147
	v_mov_b32_e32 v24, v148
	v_mov_b32_e32 v25, v149
	v_mov_b32_e32 v26, v150
	v_mov_b32_e32 v27, v151
	v_mov_b32_e32 v28, v152
	v_mov_b32_e32 v29, v153
	v_mov_b32_e32 v30, v154
	v_mov_b32_e32 v31, v155
	v_mov_b32_e32 v32, v156
	v_mov_b32_e32 v33, v157
	v_mov_b32_e32 v34, v158
	v_mov_b32_e32 v35, v159
	v_mov_b32_e32 v4, v160
	v_mov_b32_e32 v5, v161
	v_mov_b32_e32 v6, v162
	v_mov_b32_e32 v7, v163
	v_mov_b32_e32 v8, v164
	v_mov_b32_e32 v9, v165
	v_mov_b32_e32 v10, v166
	v_mov_b32_e32 v11, v167
	v_mov_b32_e32 v12, v168
	v_mov_b32_e32 v13, v169
	v_mov_b32_e32 v14, v170
	v_mov_b32_e32 v15, v171
	v_mov_b32_e32 v16, v172
	v_mov_b32_e32 v17, v173
	v_mov_b32_e32 v18, v174
	v_mov_b32_e32 v19, v175
	v_readfirstlane_b32 s53, v1
	v_add_u32_e32 v237, v192, v193
	v_add_u32_e32 v238, v181, v193
	v_add_u32_e32 v239, v192, v194
	v_add_u32_e32 v240, v181, v194
	s_add_u32 s53, s53, 16
	s_add_u32 s52, s53, 0x18000
	s_mov_b32 m0, s52
	s_nop 0
	global_load_lds_dwordx4 v[190:191], off
	s_add_u32 m0, s52, 0x400
	s_nop 0
	global_load_lds_dwordx4 v[188:189], off
	s_add_u32 m0, s52, 0x4000
	s_nop 0
	global_load_lds_dwordx4 v[186:187], off
	s_add_u32 m0, s52, 0x4400
	s_nop 0
	global_load_lds_dwordx4 v[184:185], off
	v_add_u32_e32 v241, s56, v237
	v_add_u32_e32 v242, s56, v238
	ds_read_b128 v[160:163], v241 offset:16400
	ds_read_b128 v[156:159], v241 offset:18448
	ds_read_b128 v[176:179], v242 offset:16
	ds_read_b128 v[172:175], v242 offset:2064
	ds_read_b128 v[168:171], v242 offset:4112
	ds_read_b128 v[164:167], v242 offset:6160
	s_mov_b64 s[36:37], 64
	s_waitcnt lgkmcnt(0)
.Lpl_s3:
	v_add_u32_e32 v241, s56, v239
	v_add_u32_e32 v242, s56, v240
	v_mfma_f32_32x32x16_f16 v[116:131], v[160:163], v[176:179], v[116:131]
	ds_read_b128 v[136:139], v241 offset:16400
	ds_read_b128 v[132:135], v241 offset:18448
	v_mfma_f32_32x32x16_f16 v[100:115], v[156:159], v[176:179], v[100:115]
	ds_read_b128 v[152:155], v242 offset:16
	ds_read_b128 v[148:151], v242 offset:2064
	v_mfma_f32_32x32x16_f16 v[84:99], v[160:163], v[172:175], v[84:99]
	ds_read_b128 v[144:147], v242 offset:4112
	ds_read_b128 v[140:143], v242 offset:6160
	v_mfma_f32_32x32x16_f16 v[68:83], v[156:159], v[172:175], v[68:83]
	v_mfma_f32_32x32x16_f16 v[52:67], v[160:163], v[168:171], v[52:67]
	v_mfma_f32_32x32x16_f16 v[36:51], v[156:159], v[168:171], v[36:51]
	v_mfma_f32_32x32x16_f16 v[20:35], v[160:163], v[164:167], v[20:35]
	v_mfma_f32_32x32x16_f16 v[4:19], v[156:159], v[164:167], v[4:19]
	s_waitcnt vmcnt(8) lgkmcnt(0)
	s_barrier
	s_add_i32 s55, s56, 0x8000
	s_cmp_lg_u32 s56, 0x18000
	s_cselect_b32 s55, s55, 0
	v_add_u32_e32 v241, s55, v237
	v_add_u32_e32 v242, s55, v238
	s_add_u32 s52, s53, s56
	v_mfma_f32_32x32x16_f16 v[116:131], v[136:139], v[152:155], v[116:131]
	ds_read_b128 v[160:163], v241 offset:16400
	ds_read_b128 v[156:159], v241 offset:18448
	v_mfma_f32_32x32x16_f16 v[100:115], v[132:135], v[152:155], v[100:115]
	ds_read_b128 v[176:179], v242 offset:16
	ds_read_b128 v[172:175], v242 offset:2064
	v_mfma_f32_32x32x16_f16 v[84:99], v[136:139], v[148:151], v[84:99]
	ds_read_b128 v[168:171], v242 offset:4112
	ds_read_b128 v[164:167], v242 offset:6160
	v_mfma_f32_32x32x16_f16 v[68:83], v[132:135], v[148:151], v[68:83]
	s_mov_b32 m0, s52
	v_lshl_add_u64 v[244:245], v[190:191], 0, s[36:37]
	global_load_lds_dwordx4 v[244:245], off
	v_mfma_f32_32x32x16_f16 v[52:67], v[136:139], v[144:147], v[52:67]
	s_add_u32 m0, s52, 0x400
	v_lshl_add_u64 v[246:247], v[188:189], 0, s[36:37]
	global_load_lds_dwordx4 v[246:247], off
	v_mfma_f32_32x32x16_f16 v[36:51], v[132:135], v[144:147], v[36:51]
	s_add_u32 m0, s52, 0x4000
	v_lshl_add_u64 v[244:245], v[186:187], 0, s[36:37]
	global_load_lds_dwordx4 v[244:245], off
	v_mfma_f32_32x32x16_f16 v[20:35], v[136:139], v[140:143], v[20:35]
	s_add_u32 m0, s52, 0x4400
	v_lshl_add_u64 v[246:247], v[184:185], 0, s[36:37]
	global_load_lds_dwordx4 v[246:247], off
	v_mfma_f32_32x32x16_f16 v[4:19], v[132:135], v[140:143], v[4:19]
	s_waitcnt lgkmcnt(0)
	s_mov_b32 s56, s55
	s_add_i32 s57, s57, 1
	s_add_u32 s36, s36, 64
	s_addc_u32 s37, s37, 0
	s_cmp_lt_u32 s57, 28
	s_cbranch_scc1 .Lpl_s3
	v_add_u32_e32 v241, s56, v239
	v_add_u32_e32 v242, s56, v240
	v_mfma_f32_32x32x16_f16 v[116:131], v[160:163], v[176:179], v[116:131]
	ds_read_b128 v[136:139], v241 offset:16400
	ds_read_b128 v[132:135], v241 offset:18448
	v_mfma_f32_32x32x16_f16 v[100:115], v[156:159], v[176:179], v[100:115]
	ds_read_b128 v[152:155], v242 offset:16
	ds_read_b128 v[148:151], v242 offset:2064
	v_mfma_f32_32x32x16_f16 v[84:99], v[160:163], v[172:175], v[84:99]
	ds_read_b128 v[144:147], v242 offset:4112
	ds_read_b128 v[140:143], v242 offset:6160
	v_mfma_f32_32x32x16_f16 v[68:83], v[156:159], v[172:175], v[68:83]
	v_mfma_f32_32x32x16_f16 v[52:67], v[160:163], v[168:171], v[52:67]
	v_mfma_f32_32x32x16_f16 v[36:51], v[156:159], v[168:171], v[36:51]
	v_mfma_f32_32x32x16_f16 v[20:35], v[160:163], v[164:167], v[20:35]
	v_mfma_f32_32x32x16_f16 v[4:19], v[156:159], v[164:167], v[4:19]
	s_waitcnt vmcnt(8) lgkmcnt(0)
	s_barrier
	s_add_i32 s55, s56, 0x8000
	s_cmp_lg_u32 s56, 0x18000
	s_cselect_b32 s55, s55, 0
	v_add_u32_e32 v241, s55, v237
	v_add_u32_e32 v242, s55, v238
	v_mfma_f32_32x32x16_f16 v[116:131], v[136:139], v[152:155], v[116:131]
	ds_read_b128 v[160:163], v241 offset:16400
	ds_read_b128 v[156:159], v241 offset:18448
	v_mfma_f32_32x32x16_f16 v[100:115], v[132:135], v[152:155], v[100:115]
	ds_read_b128 v[176:179], v242 offset:16
	ds_read_b128 v[172:175], v242 offset:2064
	v_mfma_f32_32x32x16_f16 v[84:99], v[136:139], v[148:151], v[84:99]
	ds_read_b128 v[168:171], v242 offset:4112
	ds_read_b128 v[164:167], v242 offset:6160
	v_mfma_f32_32x32x16_f16 v[68:83], v[132:135], v[148:151], v[68:83]
	v_mfma_f32_32x32x16_f16 v[52:67], v[136:139], v[144:147], v[52:67]
	v_mfma_f32_32x32x16_f16 v[36:51], v[132:135], v[144:147], v[36:51]
	v_mfma_f32_32x32x16_f16 v[20:35], v[136:139], v[140:143], v[20:35]
	v_mfma_f32_32x32x16_f16 v[4:19], v[132:135], v[140:143], v[4:19]
	s_waitcnt lgkmcnt(0)
	s_mov_b32 s56, s55
	v_add_u32_e32 v241, s56, v239
	v_add_u32_e32 v242, s56, v240
	v_mfma_f32_32x32x16_f16 v[116:131], v[160:163], v[176:179], v[116:131]
	ds_read_b128 v[136:139], v241 offset:16400
	ds_read_b128 v[132:135], v241 offset:18448
	v_mfma_f32_32x32x16_f16 v[100:115], v[156:159], v[176:179], v[100:115]
	ds_read_b128 v[152:155], v242 offset:16
	ds_read_b128 v[148:151], v242 offset:2064
	v_mfma_f32_32x32x16_f16 v[84:99], v[160:163], v[172:175], v[84:99]
	ds_read_b128 v[144:147], v242 offset:4112
	ds_read_b128 v[140:143], v242 offset:6160
	v_mfma_f32_32x32x16_f16 v[68:83], v[156:159], v[172:175], v[68:83]
	v_mfma_f32_32x32x16_f16 v[52:67], v[160:163], v[168:171], v[52:67]
	v_mfma_f32_32x32x16_f16 v[36:51], v[156:159], v[168:171], v[36:51]
	v_mfma_f32_32x32x16_f16 v[20:35], v[160:163], v[164:167], v[20:35]
	v_mfma_f32_32x32x16_f16 v[4:19], v[156:159], v[164:167], v[4:19]
	s_waitcnt vmcnt(4) lgkmcnt(0)
	s_barrier
	s_add_i32 s55, s56, 0x8000
	s_cmp_lg_u32 s56, 0x18000
	s_cselect_b32 s55, s55, 0
	v_add_u32_e32 v241, s55, v237
	v_add_u32_e32 v242, s55, v238
	v_mfma_f32_32x32x16_f16 v[116:131], v[136:139], v[152:155], v[116:131]
	ds_read_b128 v[160:163], v241 offset:16400
	ds_read_b128 v[156:159], v241 offset:18448
	v_mfma_f32_32x32x16_f16 v[100:115], v[132:135], v[152:155], v[100:115]
	ds_read_b128 v[176:179], v242 offset:16
	ds_read_b128 v[172:175], v242 offset:2064
	v_mfma_f32_32x32x16_f16 v[84:99], v[136:139], v[148:151], v[84:99]
	ds_read_b128 v[168:171], v242 offset:4112
	ds_read_b128 v[164:167], v242 offset:6160
	v_mfma_f32_32x32x16_f16 v[68:83], v[132:135], v[148:151], v[68:83]
	v_mfma_f32_32x32x16_f16 v[52:67], v[136:139], v[144:147], v[52:67]
	v_mfma_f32_32x32x16_f16 v[36:51], v[132:135], v[144:147], v[36:51]
	v_mfma_f32_32x32x16_f16 v[20:35], v[136:139], v[140:143], v[20:35]
	v_mfma_f32_32x32x16_f16 v[4:19], v[132:135], v[140:143], v[4:19]
	s_waitcnt lgkmcnt(0)
	s_mov_b32 s56, s55
	v_add_u32_e32 v241, s56, v239
	v_add_u32_e32 v242, s56, v240
	v_mfma_f32_32x32x16_f16 v[116:131], v[160:163], v[176:179], v[116:131]
	ds_read_b128 v[136:139], v241 offset:16400
	ds_read_b128 v[132:135], v241 offset:18448
	v_mfma_f32_32x32x16_f16 v[100:115], v[156:159], v[176:179], v[100:115]
	ds_read_b128 v[152:155], v242 offset:16
	ds_read_b128 v[148:151], v242 offset:2064
	v_mfma_f32_32x32x16_f16 v[84:99], v[160:163], v[172:175], v[84:99]
	ds_read_b128 v[144:147], v242 offset:4112
	ds_read_b128 v[140:143], v242 offset:6160
	v_mfma_f32_32x32x16_f16 v[68:83], v[156:159], v[172:175], v[68:83]
	v_mfma_f32_32x32x16_f16 v[52:67], v[160:163], v[168:171], v[52:67]
	v_mfma_f32_32x32x16_f16 v[36:51], v[156:159], v[168:171], v[36:51]
	v_mfma_f32_32x32x16_f16 v[20:35], v[160:163], v[164:167], v[20:35]
	v_mfma_f32_32x32x16_f16 v[4:19], v[156:159], v[164:167], v[4:19]
	s_waitcnt vmcnt(0) lgkmcnt(0)
	s_barrier
	s_add_i32 s55, s56, 0x8000
	s_cmp_lg_u32 s56, 0x18000
	s_cselect_b32 s55, s55, 0
	v_add_u32_e32 v241, s55, v237
	v_add_u32_e32 v242, s55, v238
	v_mfma_f32_32x32x16_f16 v[116:131], v[136:139], v[152:155], v[116:131]
	ds_read_b128 v[160:163], v241 offset:16400
	ds_read_b128 v[156:159], v241 offset:18448
	v_mfma_f32_32x32x16_f16 v[100:115], v[132:135], v[152:155], v[100:115]
	ds_read_b128 v[176:179], v242 offset:16
	ds_read_b128 v[172:175], v242 offset:2064
	v_mfma_f32_32x32x16_f16 v[84:99], v[136:139], v[148:151], v[84:99]
	ds_read_b128 v[168:171], v242 offset:4112
	ds_read_b128 v[164:167], v242 offset:6160
	v_mfma_f32_32x32x16_f16 v[68:83], v[132:135], v[148:151], v[68:83]
	v_mfma_f32_32x32x16_f16 v[52:67], v[136:139], v[144:147], v[52:67]
	v_mfma_f32_32x32x16_f16 v[36:51], v[132:135], v[144:147], v[36:51]
	v_mfma_f32_32x32x16_f16 v[20:35], v[136:139], v[140:143], v[20:35]
	v_mfma_f32_32x32x16_f16 v[4:19], v[132:135], v[140:143], v[4:19]
	s_waitcnt lgkmcnt(0)
	s_mov_b32 s56, s55
	v_add_u32_e32 v241, s56, v239
	v_add_u32_e32 v242, s56, v240
	v_mfma_f32_32x32x16_f16 v[116:131], v[160:163], v[176:179], v[116:131]
	ds_read_b128 v[136:139], v241 offset:16400
	ds_read_b128 v[132:135], v241 offset:18448
	v_mfma_f32_32x32x16_f16 v[100:115], v[156:159], v[176:179], v[100:115]
	ds_read_b128 v[152:155], v242 offset:16
	ds_read_b128 v[148:151], v242 offset:2064
	v_mfma_f32_32x32x16_f16 v[84:99], v[160:163], v[172:175], v[84:99]
	ds_read_b128 v[144:147], v242 offset:4112
	ds_read_b128 v[140:143], v242 offset:6160
	v_mfma_f32_32x32x16_f16 v[68:83], v[156:159], v[172:175], v[68:83]
	v_mfma_f32_32x32x16_f16 v[52:67], v[160:163], v[168:171], v[52:67]
	v_mfma_f32_32x32x16_f16 v[36:51], v[156:159], v[168:171], v[36:51]
	v_mfma_f32_32x32x16_f16 v[20:35], v[160:163], v[164:167], v[20:35]
	v_mfma_f32_32x32x16_f16 v[4:19], v[156:159], v[164:167], v[4:19]
	s_waitcnt lgkmcnt(0)
	s_barrier
	v_mfma_f32_32x32x16_f16 v[116:131], v[136:139], v[152:155], v[116:131]
	v_mfma_f32_32x32x16_f16 v[100:115], v[132:135], v[152:155], v[100:115]
	v_mfma_f32_32x32x16_f16 v[84:99], v[136:139], v[148:151], v[84:99]
	v_mfma_f32_32x32x16_f16 v[68:83], v[132:135], v[148:151], v[68:83]
	v_mfma_f32_32x32x16_f16 v[52:67], v[136:139], v[144:147], v[52:67]
	v_mfma_f32_32x32x16_f16 v[36:51], v[132:135], v[144:147], v[36:51]
	v_mfma_f32_32x32x16_f16 v[20:35], v[136:139], v[140:143], v[20:35]
	v_mfma_f32_32x32x16_f16 v[4:19], v[132:135], v[140:143], v[4:19]
	s_mov_b32 s56, 0
	s_mov_b32 s55, 0x18000
	s_mov_b32 s57, 32
	s_mov_b64 s[36:37], 0x800
	s_branch .LBB0_724

	.amdhsa_kernel _Z2mk6Params
		.amdhsa_group_segment_fixed_size 16
		.amdhsa_private_segment_fixed_size 0
		.amdhsa_kernarg_size 544
		.amdhsa_user_sgpr_count 2
		.amdhsa_user_sgpr_dispatch_ptr 0
		.amdhsa_user_sgpr_queue_ptr 0
		.amdhsa_user_sgpr_kernarg_segment_ptr 1
		.amdhsa_user_sgpr_dispatch_id 0
		.amdhsa_user_sgpr_kernarg_preload_length 0
		.amdhsa_user_sgpr_kernarg_preload_offset 0
		.amdhsa_user_sgpr_private_segment_size 0
		.amdhsa_uses_dynamic_stack 0
		.amdhsa_enable_private_segment 0
		.amdhsa_system_sgpr_workgroup_id_x 1
		.amdhsa_system_sgpr_workgroup_id_y 0
		.amdhsa_system_sgpr_workgroup_id_z 0
		.amdhsa_system_sgpr_workgroup_info 0
		.amdhsa_system_vgpr_workitem_id 2
		.amdhsa_next_free_vgpr 248
		.amdhsa_next_free_sgpr 100
		.amdhsa_accum_offset 248
		.amdhsa_reserve_vcc 1
		.amdhsa_float_round_mode_32 0
		.amdhsa_float_round_mode_16_64 0
		.amdhsa_float_denorm_mode_32 3
		.amdhsa_float_denorm_mode_16_64 3
		.amdhsa_dx10_clamp 1
		.amdhsa_ieee_mode 1
		.amdhsa_fp16_overflow 0
		.amdhsa_tg_split 0
		.amdhsa_exception_fp_ieee_invalid_op 0
		.amdhsa_exception_fp_denorm_src 0
		.amdhsa_exception_fp_ieee_div_zero 0
		.amdhsa_exception_fp_ieee_overflow 0
		.amdhsa_exception_fp_ieee_underflow 0
		.amdhsa_exception_fp_ieee_inexact 0
		.amdhsa_exception_int_div_zero 0
	.end_amdhsa_kernel

amdhsa.kernels:
  - .agpr_count:     0
    .args:
      - .offset:         0
        .size:           288
        .value_kind:     by_value
      - .offset:         288
        .size:           4
        .value_kind:     hidden_block_count_x
      - .offset:         292
        .size:           4
        .value_kind:     hidden_block_count_y
      - .offset:         296
        .size:           4
        .value_kind:     hidden_block_count_z
      - .offset:         300
        .size:           2
        .value_kind:     hidden_group_size_x
      - .offset:         302
        .size:           2
        .value_kind:     hidden_group_size_y
      - .offset:         304
        .size:           2
        .value_kind:     hidden_group_size_z
      - .offset:         306
        .size:           2
        .value_kind:     hidden_remainder_x
      - .offset:         308
        .size:           2
        .value_kind:     hidden_remainder_y
      - .offset:         310
        .size:           2
        .value_kind:     hidden_remainder_z
      - .offset:         328
        .size:           8
        .value_kind:     hidden_global_offset_x
      - .offset:         336
        .size:           8
        .value_kind:     hidden_global_offset_y
      - .offset:         344
        .size:           8
        .value_kind:     hidden_global_offset_z
      - .offset:         352
        .size:           2
        .value_kind:     hidden_grid_dims
      - .offset:         376
        .size:           8
        .value_kind:     hidden_multigrid_sync_arg
      - .offset:         408
        .size:           4
        .value_kind:     hidden_dynamic_lds_size
    .group_segment_fixed_size: 16
    .kernarg_segment_align: 8
    .kernarg_segment_size: 544
    .language:       OpenCL C
    .language_version:
      - 2
      - 0
    .max_flat_workgroup_size: 512
    .name:           _Z2mk6Params
    .private_segment_fixed_size: 0
    .sgpr_count:     106
    .sgpr_spill_count: 149
    .symbol:         _Z2mk6Params.kd
    .uniform_work_group_size: 1
    .uses_dynamic_stack: false
    .vgpr_count:     248
    .vgpr_spill_count: 0
    .wavefront_size: 64
